# forget-gate cumsum phase: coalesced loads of the log-gate column (consecutive lanes = consecutive positions) transposed through LDS instead of 16 loads per thread strided 32 B with threads 512 B apart
# speedup vs baseline: 1.0038x; 1.0038x over previous
; #define LAS __attribute__((address_space(3)))
; __device__ __forceinline__ int rfl(int v) { return __builtin_amdgcn_readfirstlane(v); }
; __device__ __forceinline__ void phase_cumsum(const Params& p, LAS unsigned char* lds) {
;     if (blockIdx.x >= 64) return;
;     const int tid = threadIdx.x, lane = tid & 63, wid = rfl(tid >> 6);
;     const int b = blockIdx.x >> 3, h = blockIdx.x & 7;
;     const float* LF = (const float*)(p.ws + WS_LF); float* F2 = (float*)(p.ws + WS_F2) + (size_t)blockIdx.x * SEQ;
;     LAS double* wt = (LAS double*)lds;
;     float v[16]; float run = 0.f; const int s0 = 16 * tid;
; #pragma unroll
;     for (int i = 0; i < 16; ++i) { run += LF[((size_t)b * SEQ + s0 + i) * 8 + h]; v[i] = run; }
.LBB0_896:
	s_or_b64 exec, exec, s[0:1]
	s_cmp_gt_i32 s64, 7
	s_cselect_b64 s[0:1], -1, 0
	s_cmp_lt_i32 s65, 8
	s_cselect_b64 s[4:5], -1, 0
	s_or_b64 s[0:1], s[0:1], s[4:5]
	s_cmp_gt_u32 s76, 63
	s_cselect_b64 s[4:5], -1, 0
	s_or_b64 s[0:1], s[4:5], s[0:1]
	s_and_b64 vcc, exec, s[0:1]
	s_waitcnt lgkmcnt(0)
	s_barrier
	s_cbranch_vccnz .LBB0_908
	s_load_dwordx2 s[0:1], s[78:79], 0xa0
	s_and_b32 s2, s76, 7
	s_lshl_b32 s4, s76, 10
	s_and_b32 s6, s4, 0xe000
	s_lshl_b32 s2, s2, 2
	s_waitcnt vmcnt(4)
	v_lshlrev_b32_e32 v2, 4, v144
	s_waitcnt lgkmcnt(0)
	s_add_u32 s4, s0, s2
	s_addc_u32 s5, s1, 0
	v_add_lshl_u32 v0, s6, v2, 5
	v_mov_b32_e32 v1, 0
	v_lshl_add_u64 v[0:1], s[4:5], 0, v[0:1]
	s_mov_b64 s[4:5], 0x800000
	s_mov_b32 s2, 0x800000
	s_waitcnt vmcnt(3)
	v_lshl_add_u64 v[4:5], v[0:1], 0, s[4:5]
	v_add_co_u32_e32 v0, vcc, s2, v0
	v_and_b32_e32 v22, 63, v144
	s_nop 0
	v_addc_co_u32_e32 v1, vcc, 0, v1, vcc
	v_mul_u32_u24_e32 v56, 0x1e0, v144
	v_sub_co_u32_e32 v58, vcc, v4, v56
	s_nop 1
	v_subbrev_co_u32_e32 v59, vcc, 0, v5, vcc
	s_mov_b64 s[98:99], 0x4000
	global_load_dword v40, v[58:59], off
	v_lshl_add_u64 v[58:59], v[58:59], 0, s[98:99]
	global_load_dword v41, v[58:59], off
	v_lshl_add_u64 v[58:59], v[58:59], 0, s[98:99]
	global_load_dword v42, v[58:59], off
	v_lshl_add_u64 v[58:59], v[58:59], 0, s[98:99]
	global_load_dword v43, v[58:59], off
	v_lshl_add_u64 v[58:59], v[58:59], 0, s[98:99]
	global_load_dword v44, v[58:59], off
	v_lshl_add_u64 v[58:59], v[58:59], 0, s[98:99]
	global_load_dword v45, v[58:59], off
	v_lshl_add_u64 v[58:59], v[58:59], 0, s[98:99]
	global_load_dword v46, v[58:59], off
	v_lshl_add_u64 v[58:59], v[58:59], 0, s[98:99]
	global_load_dword v47, v[58:59], off
	v_lshl_add_u64 v[58:59], v[58:59], 0, s[98:99]
	global_load_dword v48, v[58:59], off
	v_lshl_add_u64 v[58:59], v[58:59], 0, s[98:99]
	global_load_dword v49, v[58:59], off
	v_lshl_add_u64 v[58:59], v[58:59], 0, s[98:99]
	global_load_dword v50, v[58:59], off
	v_lshl_add_u64 v[58:59], v[58:59], 0, s[98:99]
	global_load_dword v51, v[58:59], off
	v_lshl_add_u64 v[58:59], v[58:59], 0, s[98:99]
	global_load_dword v52, v[58:59], off
	v_lshl_add_u64 v[58:59], v[58:59], 0, s[98:99]
	global_load_dword v53, v[58:59], off
	v_lshl_add_u64 v[58:59], v[58:59], 0, s[98:99]
	global_load_dword v54, v[58:59], off
	v_lshl_add_u64 v[58:59], v[58:59], 0, s[98:99]
	global_load_dword v55, v[58:59], off
	v_lshlrev_b32_e32 v57, 2, v144
	v_add_u32_e32 v57, 0x1000, v57
	s_waitcnt vmcnt(15)
	ds_write_b32 v57, v40
	s_waitcnt vmcnt(14)
	ds_write_b32 v57, v41 offset:2048
	s_waitcnt vmcnt(13)
	ds_write_b32 v57, v42 offset:4096
	s_waitcnt vmcnt(12)
	ds_write_b32 v57, v43 offset:6144
	s_waitcnt vmcnt(11)
	ds_write_b32 v57, v44 offset:8192
	s_waitcnt vmcnt(10)
	ds_write_b32 v57, v45 offset:10240
	s_waitcnt vmcnt(9)
	ds_write_b32 v57, v46 offset:12288
	s_waitcnt vmcnt(8)
	ds_write_b32 v57, v47 offset:14336
	s_waitcnt vmcnt(7)
	ds_write_b32 v57, v48 offset:16384
	s_waitcnt vmcnt(6)
	ds_write_b32 v57, v49 offset:18432
	s_waitcnt vmcnt(5)
	ds_write_b32 v57, v50 offset:20480
	s_waitcnt vmcnt(4)
	ds_write_b32 v57, v51 offset:22528
	s_waitcnt vmcnt(3)
	ds_write_b32 v57, v52 offset:24576
	s_waitcnt vmcnt(2)
	ds_write_b32 v57, v53 offset:26624
	s_waitcnt vmcnt(1)
	ds_write_b32 v57, v54 offset:28672
	s_waitcnt vmcnt(0)
	ds_write_b32 v57, v55 offset:30720
	s_waitcnt lgkmcnt(0)
	s_barrier
; #define LAS __attribute__((address_space(3)))
; __device__ __forceinline__ void phase_cumsum(const Params& p, LAS unsigned char* lds) {
;     ...
;     LAS double* wt = (LAS double*)lds;
;     float v[16]; float run = 0.f; const int s0 = 16 * tid;
; #pragma unroll
;     for (int i = 0; i < 16; ++i) { run += LF[((size_t)b * SEQ + s0 + i) * 8 + h]; v[i] = run; }
;     double inc = (double)run;
; #pragma unroll
;     for (int o = 1; o < 64; o <<= 1) { const double t = __shfl_up(inc, o); if (lane >= o) inc += t; }
;     if (lane == 63) wt[wid] = inc;
;     __syncthreads();
;     double pre = inc - (double)run;
;     for (int w = 0; w < wid; ++w) pre += wt[w];
	v_lshlrev_b32_e32 v57, 6, v144
	v_add_u32_e32 v57, 0x1000, v57
	ds_read_b32 v3, v57
	ds_read_b32 v6, v57 offset:4
	ds_read_b32 v7, v57 offset:8
	ds_read_b32 v8, v57 offset:12
	ds_read_b32 v9, v57 offset:16
	ds_read_b32 v10, v57 offset:20
	ds_read_b32 v11, v57 offset:24
	ds_read_b32 v12, v57 offset:28
	ds_read_b32 v13, v57 offset:32
	ds_read_b32 v14, v57 offset:36
	ds_read_b32 v23, v57 offset:40
	ds_read_b32 v24, v57 offset:44
	ds_read_b32 v25, v57 offset:48
	ds_read_b32 v26, v57 offset:52
	ds_read_b32 v27, v57 offset:56
	ds_read_b32 v0, v57 offset:60
	s_waitcnt lgkmcnt(0)
	s_nop 0
	s_nop 0
	v_mbcnt_lo_u32_b32 v1, -1, 0
	v_mbcnt_hi_u32_b32 v28, -1, v1
	v_and_b32_e32 v29, 64, v28
	v_add_u32_e32 v1, -1, v28
	v_cmp_lt_i32_e32 vcc, v1, v29
	v_readfirstlane_b32 s2, v144
	s_lshr_b32 s6, s2, 6
	v_cndmask_b32_e32 v1, v1, v28, vcc
	v_lshlrev_b32_e32 v5, 2, v1
	s_waitcnt vmcnt(15)
	v_add_f32_e32 v3, 0, v3
	s_waitcnt vmcnt(14)
	v_add_f32_e32 v21, v3, v6
	s_waitcnt vmcnt(13)
	v_add_f32_e32 v19, v21, v7
	s_waitcnt vmcnt(12)
	v_add_f32_e32 v20, v19, v8
	s_waitcnt vmcnt(11)
	v_add_f32_e32 v17, v20, v9
	s_waitcnt vmcnt(10)
	v_add_f32_e32 v18, v17, v10
	s_waitcnt vmcnt(9)
	v_add_f32_e32 v15, v18, v11
	s_waitcnt vmcnt(8)
	v_add_f32_e32 v16, v15, v12
	s_waitcnt vmcnt(7)
	v_add_f32_e32 v13, v16, v13
	s_waitcnt vmcnt(6)
	v_add_f32_e32 v14, v13, v14
	s_waitcnt vmcnt(5)
	v_add_f32_e32 v11, v14, v23
	s_waitcnt vmcnt(4)
	v_add_f32_e32 v12, v11, v24
	s_waitcnt vmcnt(3)
	v_add_f32_e32 v9, v12, v25
	s_waitcnt vmcnt(2)
	v_add_f32_e32 v10, v9, v26
	s_waitcnt vmcnt(1)
	v_add_f32_e32 v8, v10, v27
	v_add_u32_e32 v6, -2, v28
	s_waitcnt vmcnt(0)
	v_add_f32_e32 v0, v8, v0
	v_cvt_f64_f32_e32 v[0:1], v0
	ds_bpermute_b32 v4, v5, v0
	ds_bpermute_b32 v5, v5, v1
	v_cmp_lt_i32_e32 vcc, v6, v29
	v_add_u32_e32 v23, -4, v28
	s_waitcnt lgkmcnt(0)
	v_add_f64 v[4:5], v[0:1], v[4:5]
	v_cndmask_b32_e32 v6, v6, v28, vcc
	v_cmp_eq_u32_e32 vcc, 0, v22
	v_lshlrev_b32_e32 v7, 2, v6
	s_nop 0
	v_cndmask_b32_e32 v5, v5, v1, vcc
	v_cndmask_b32_e32 v4, v4, v0, vcc
	ds_bpermute_b32 v6, v7, v4
	ds_bpermute_b32 v7, v7, v5
	v_cmp_lt_i32_e32 vcc, v23, v29
	s_waitcnt lgkmcnt(0)
	v_add_f64 v[6:7], v[4:5], v[6:7]
	v_cndmask_b32_e32 v23, v23, v28, vcc
	v_cmp_gt_u32_e32 vcc, 2, v22
	v_lshlrev_b32_e32 v23, 2, v23
	s_nop 0
	v_cndmask_b32_e32 v5, v7, v5, vcc
	v_cndmask_b32_e32 v4, v6, v4, vcc
	ds_bpermute_b32 v6, v23, v4
	ds_bpermute_b32 v7, v23, v5
	v_add_u32_e32 v23, -8, v28
	v_cmp_lt_i32_e32 vcc, v23, v29
	s_waitcnt lgkmcnt(0)
	v_add_f64 v[6:7], v[4:5], v[6:7]
	v_cndmask_b32_e32 v23, v23, v28, vcc
	v_cmp_gt_u32_e32 vcc, 4, v22
	v_lshlrev_b32_e32 v23, 2, v23
	s_nop 0
	v_cndmask_b32_e32 v5, v7, v5, vcc
	v_cndmask_b32_e32 v4, v6, v4, vcc
	ds_bpermute_b32 v6, v23, v4
	ds_bpermute_b32 v7, v23, v5
	v_add_u32_e32 v23, -16, v28
	v_cmp_lt_i32_e32 vcc, v23, v29
	s_waitcnt lgkmcnt(0)
	v_add_f64 v[6:7], v[4:5], v[6:7]
	v_cndmask_b32_e32 v23, v23, v28, vcc
	v_cmp_gt_u32_e32 vcc, 8, v22
	v_lshlrev_b32_e32 v23, 2, v23
	s_nop 0
	v_cndmask_b32_e32 v5, v7, v5, vcc
	v_cndmask_b32_e32 v4, v6, v4, vcc
	ds_bpermute_b32 v6, v23, v4
	ds_bpermute_b32 v7, v23, v5
	v_subrev_u32_e32 v23, 32, v28
	v_cmp_lt_i32_e32 vcc, v23, v29
	s_waitcnt lgkmcnt(0)
	v_add_f64 v[6:7], v[4:5], v[6:7]
	v_cndmask_b32_e32 v23, v23, v28, vcc
	v_cmp_gt_u32_e32 vcc, 16, v22
	v_lshlrev_b32_e32 v23, 2, v23
	s_nop 0
	v_cndmask_b32_e32 v5, v7, v5, vcc
	v_cndmask_b32_e32 v4, v6, v4, vcc
	ds_bpermute_b32 v6, v23, v4
	ds_bpermute_b32 v7, v23, v5
	v_cmp_eq_u32_e32 vcc, 63, v22
	s_waitcnt lgkmcnt(0)
	v_add_f64 v[6:7], v[4:5], v[6:7]
	s_and_saveexec_b64 s[4:5], vcc
	s_lshl_b32 s7, s6, 3
	s_addk_i32 s7, 0x100
	v_mov_b32_e32 v23, s7
	ds_write_b64 v23, v[6:7]
	s_or_b64 exec, exec, s[4:5]
	v_cmp_gt_u32_e32 vcc, 32, v22
	s_cmp_lt_u32 s2, 64
	s_waitcnt lgkmcnt(0)
	v_cndmask_b32_e32 v5, v7, v5, vcc
	v_cndmask_b32_e32 v4, v6, v4, vcc
	v_add_f64 v[4:5], v[4:5], -v[0:1]
	s_barrier
	s_cbranch_scc1 .LBB0_907
	s_add_i32 s4, s6, -1
	s_cmp_lt_u32 s4, 7
	s_cbranch_scc1 .LBB0_904
	s_and_b32 s4, s6, 0x3fffff8
	s_mov_b32 s5, 0
	s_movk_i32 s6, 0x100
